# k16 plus stick-breaking attention prologue de-serialised (tile-1 loads issued with tile-0) and a static priority raise for waves 0-3 during the attention loop
# speedup vs baseline: 1.0092x; 1.0014x over previous
;     __device__ __forceinline__ unsigned char* ws() const { return (unsigned char*)(__attribute__((address_space(1))) unsigned char*)get(21); }
; template <int l>
; __device__ __forceinline__ void layer_body(const Ptrs& A, LAS unsigned char* lds, unsigned char* lds_raw, const int wv0) {
;     ...
;         if (PH(4)) {
;             if (l == 0) memkv_post(A, gw, NGW, lane);
;             for (int u = c; u < 256 * (1 + DUP_ATTN); u += G) {
;                 const int head = (u & 255) >> 5, p = u & 31;
;                 const bf16* Q = (const bf16*)(ws + WS_SQ) + head * 128; const bf16* Kp = (const bf16*)(ws + WS_SK) + head * 128; const bf16* V = (const bf16*)(ws + WS_SV) + head * 128;
;                 bf16* O = (bf16*)(ws + WS_ABR) + (size_t)T * 1024 + head * 128;
; #pragma unroll 1
;                 for (int rep = 0; rep < 2; ++rep) sba::sb_unit(Q, Kp, V, O, (rep ? p : 63 - p) * 256, (char*)lds_raw, wv0);
.LBB0_279:
	v_writelane_b32 v255, s70, 0
	s_nop 1
	v_writelane_b32 v255, s71, 1
	s_or_b64 exec, exec, s[0:1]
	s_cmpk_gt_i32 s80, 0xff
	s_cbranch_scc1 .LBB0_296
	v_readfirstlane_b32 s97, v204
	s_lshr_b32 s97, s97, 6
	s_cmp_lt_u32 s97, 4
	s_cbranch_scc0 .Lsbprio_done1
	s_setprio 1
.Lsbprio_done1:
	s_mov_b64 s[46:47], src_shared_base
	s_add_u32 s46, s44, 0x13a00000
	s_addc_u32 s81, s45, 0
	s_add_u32 s82, s44, 0x15a00000
	s_addc_u32 s83, s45, 0
	s_add_u32 s84, s44, 0x17a00000
	s_addc_u32 s85, s45, 0
	s_add_u32 s86, s44, 0x29a00000
	s_mov_b32 s48, 0xfffc0000
	s_addc_u32 s87, s45, 0
	s_lshl_b32 s88, s80, 2
	s_lshl_b32 s89, s79, 2
	v_mov_b32_e32 v161, 0
	s_mov_b32 s49, -1
	s_add_i32 s90, 0, 0x10000
	s_movk_i32 s91, 0x7fff
	s_mov_b32 s92, 0xd000
	s_branch .LBB0_282

; #define TID() (wv0 * 64 + (int)__builtin_amdgcn_mbcnt_hi(~0u, __builtin_amdgcn_mbcnt_lo(~0u, 0u)))
; __device__ __forceinline__ int opaque(int x) { asm volatile("" : "+v"(x)); return x; }
;     __device__ __forceinline__ unsigned char* ws() const { return (unsigned char*)(__attribute__((address_space(1))) unsigned char*)get(21); }
; __device__ __forceinline__ void gla_scan(const Ptrs& A, const int wv0) {
;     const int tid = opaque(TID());
;     unsigned char* ws = A.ws();
;     for (int g = blockIdx.x * 512 + tid; g < 131072; g += gridDim.x * 512) {
;         const int hd = g >> 15, v = (g >> 7) & 255, d = g & 127;
;         bf16* us = (bf16*)(ws + WS_H) + ((size_t)hd * 256 + v) * 128 + d;
;         const float* dec = (const float*)(ws + WS_DEC) + hd * 128 + d;
;         float st = 0.f;
; template <int l>
; __device__ __forceinline__ void layer_body(const Ptrs& A, LAS unsigned char* lds, unsigned char* lds_raw, const int wv0) {
;     ...
;             }
;             __syncthreads();
;             gla_scan(A, wv0);
.LBB0_296:
	s_setprio 0
	v_mov_b32_e32 v0, v204
	s_waitcnt vmcnt(63) expcnt(7) lgkmcnt(15)
	s_barrier
	v_mov_b32 v1, s77
	ds_read_b64 v[2:3], v1 offset:168
	s_lshl_b32 s96, s33, 9
	v_add_u32_e32 v1, s96, v0
	s_mov_b32 s0, 0x20000
	v_cmp_gt_i32_e32 vcc, s0, v1
	s_waitcnt lgkmcnt(0)
	v_readfirstlane_b32 s5, v3
	v_readfirstlane_b32 s4, v2
	s_and_saveexec_b64 s[6:7], vcc
	s_cbranch_execz .LBB0_301
	v_and_b32_e32 v2, 0x7f, v0
	s_lshl_b32 s14, s76, 9
	v_lshlrev_b32_e32 v0, 1, v2
	v_lshlrev_b32_e32 v2, 2, v2
	s_mov_b64 s[8:9], 0
	s_mov_b32 s15, 0xff00
	s_movk_i32 s16, 0x7fff
	s_mov_b64 s[10:11], 0x1000000
	s_mov_b64 s[12:13], 0x20000
	s_mov_b32 s17, 0x1ffff

;     __device__ __forceinline__ unsigned char* ws() const { return (unsigned char*)(__attribute__((address_space(1))) unsigned char*)get(21); }
; template <int l>
; __device__ __forceinline__ void layer_body(const Ptrs& A, LAS unsigned char* lds, unsigned char* lds_raw, const int wv0) {
;     ...
;         if (PH(4)) {
;             if (l == 0) memkv_post(A, gw, NGW, lane);
;             for (int u = c; u < 256 * (1 + DUP_ATTN); u += G) {
;                 const int head = (u & 255) >> 5, p = u & 31;
;                 const bf16* Q = (const bf16*)(ws + WS_SQ) + head * 128; const bf16* Kp = (const bf16*)(ws + WS_SK) + head * 128; const bf16* V = (const bf16*)(ws + WS_SV) + head * 128;
;                 bf16* O = (bf16*)(ws + WS_ABR) + (size_t)T * 1024 + head * 128;
; #pragma unroll 1
;                 for (int rep = 0; rep < 2; ++rep) sba::sb_unit(Q, Kp, V, O, (rep ? p : 63 - p) * 256, (char*)lds_raw, wv0);
.LBB0_1220:
	s_or_b64 exec, exec, s[0:1]
	s_waitcnt lgkmcnt(0)
	s_barrier
	v_mov_b32 v0, s77
	ds_read_b64 v[0:1], v0 offset:168
	s_mov_b32 s80, s76
	s_mov_b32 s81, s33
	s_waitcnt lgkmcnt(0)
	v_readfirstlane_b32 s45, v1
	v_readfirstlane_b32 s44, v0
	v_mov_b32_e32 v0, v204
	s_cmpk_gt_i32 s81, 0xff
	s_cbranch_scc1 .LBB0_1237
	v_readfirstlane_b32 s97, v204
	s_lshr_b32 s97, s97, 6
	s_cmp_lt_u32 s97, 4
	s_cbranch_scc0 .Lsbprio_done0
	s_setprio 1
.Lsbprio_done0:
	s_mov_b64 s[46:47], src_shared_base
	s_add_u32 s46, s44, 0x13a00000
	s_addc_u32 s82, s45, 0
	s_add_u32 s83, s44, 0x15a00000
	s_addc_u32 s84, s45, 0
	s_add_u32 s85, s44, 0x17a00000
	s_addc_u32 s86, s45, 0
	s_add_u32 s87, s44, 0x29a00000
	s_mov_b32 s48, 0xfffc0000
	s_addc_u32 s88, s45, 0
	s_lshl_b32 s89, s81, 2
	s_lshl_b32 s90, s80, 2
	v_mov_b32_e32 v161, 0
	s_mov_b32 s49, -1
	s_movk_i32 s91, 0x7fff
	s_branch .LBB0_1223

; #define TID() (wv0 * 64 + (int)__builtin_amdgcn_mbcnt_hi(~0u, __builtin_amdgcn_mbcnt_lo(~0u, 0u)))
; __device__ __forceinline__ int opaque(int x) { asm volatile("" : "+v"(x)); return x; }
;     __device__ __forceinline__ unsigned char* ws() const { return (unsigned char*)(__attribute__((address_space(1))) unsigned char*)get(21); }
; __device__ __forceinline__ void gla_scan(const Ptrs& A, const int wv0) {
;     const int tid = opaque(TID());
;     unsigned char* ws = A.ws();
;     for (int g = blockIdx.x * 512 + tid; g < 131072; g += gridDim.x * 512) {
;         const int hd = g >> 15, v = (g >> 7) & 255, d = g & 127;
;         bf16* us = (bf16*)(ws + WS_H) + ((size_t)hd * 256 + v) * 128 + d;
;         const float* dec = (const float*)(ws + WS_DEC) + hd * 128 + d;
;         float st = 0.f;
; template <int l>
; __device__ __forceinline__ void layer_body(const Ptrs& A, LAS unsigned char* lds, unsigned char* lds_raw, const int wv0) {
;     ...
;             }
;             __syncthreads();
;             gla_scan(A, wv0);
.LBB0_1237:
	s_setprio 0
	v_mov_b32_e32 v0, v204
	s_waitcnt vmcnt(63) expcnt(7) lgkmcnt(15)
	s_barrier
	v_mov_b32 v1, s77
	ds_read_b64 v[2:3], v1 offset:168
	v_add_u32_e32 v1, s96, v0
	s_mov_b32 s0, 0x20000
	v_cmp_gt_i32_e32 vcc, s0, v1
	s_waitcnt lgkmcnt(0)
	v_readfirstlane_b32 s5, v3
	v_readfirstlane_b32 s4, v2
	s_and_saveexec_b64 s[6:7], vcc
	v_readlane_b32 s94, v255, 0
	v_readlane_b32 s95, v255, 1
	s_cbranch_execz .LBB0_1242
	v_and_b32_e32 v2, 0x7f, v0
	s_lshl_b32 s14, s76, 9
	v_lshlrev_b32_e32 v0, 1, v2
	v_lshlrev_b32_e32 v2, 2, v2
	s_mov_b64 s[8:9], 0
	s_mov_b32 s15, 0xff00
	s_movk_i32 s16, 0x7fff
	s_mov_b64 s[10:11], 0x1000000
	s_mov_b64 s[12:13], 0x20000
	s_mov_b32 s17, 0x1ffff
